# attention item loop: K/V/Q tile prefetch two items ahead (two alternating register sets, store/load-aware loop-top vmcnt)
# speedup vs baseline: 1.0041x; 1.0019x over previous
.LBB0_405:
	v_lshlrev_b32_e32 v40, 4, v209
	v_lshlrev_b32_e32 v124, 2, v193
	v_bfe_u32 v42, v209, 2, 2
	v_and_b32_e32 v40, 0x70, v40
	s_movk_i32 s18, 0x90
	v_or_b32_e32 v123, v124, v42
	v_lshlrev_b32_e32 v42, 3, v189
	v_add_u32_e32 v118, 0, v40
	v_mul_lo_u32 v40, v112, s18
	v_mul_lo_u32 v41, v113, s18
	v_and_b32_e32 v125, 24, v42
	v_or_b32_e32 v131, 0x60, v42
	v_sub_u32_e32 v42, v189, v124
	v_lshl_add_u64 v[120:121], s[68:69], 0, v[116:117]
	v_lshl_add_u32 v122, v193, 4, 0
	v_or_b32_e32 v130, 16, v123
	v_or_b32_e32 v132, 1, v124
	v_or_b32_e32 v133, 2, v124
	v_or_b32_e32 v134, 3, v124
	v_or_b32_e32 v135, 16, v124
	v_or_b32_e32 v136, 17, v124
	v_or_b32_e32 v137, 18, v124
	v_or_b32_e32 v138, 19, v124
	v_cmp_eq_u32_e64 s[4:5], 0, v193
	v_add_u32_e32 v139, 0x6d, v42
	v_add_u32_e32 v140, v118, v40
	v_add_u32_e32 v141, v118, v41
	s_movk_i32 s19, 0x81
	s_mov_b32 s30, 0xff800000
	v_mov_b32_e32 v142, 0x90
	v_mov_b32_e32 v143, 0x80
	v_mov_b32_e32 v126, 0x3e38aa3b
	v_mov_b32_e32 v144, 0xff800000
	s_mov_b32 s16, s0
	s_mov_b32 s53, 0
	s_mov_b32 s32, 1
	s_add_i32 s59, s16, 1
	s_cmp_ge_i32 s59, s8
	s_cbranch_scc1 .LBB0_407
	s_mov_b64 s[60:61], s[2:3]
	s_mul_hi_i32 s2, s59, 0x2aaaaaab
	s_lshr_b32 s3, s2, 31
	s_ashr_i32 s2, s2, 4
	s_add_i32 s12, s2, s3
	s_mul_i32 s2, s12, 0xffffffa0
	s_add_i32 s3, s2, s59
	s_ashr_i32 s3, s3, 4
	s_and_b32 s40, s3, -2
	s_and_b32 s33, s59, 31
	s_sub_i32 s34, 5, s40
	s_lshr_b32 s3, 32, s40
	s_lshr_b32 s34, s33, s34
	s_mul_i32 s3, s34, s3
	s_sub_i32 s3, s33, s3
	s_ashr_i32 s2, s12, 3
	s_lshl_b32 s33, s3, 7
	s_ashr_i32 s3, s2, 31
	v_add_u32_e32 v224, s33, v112
	s_lshl_b64 s[2:3], s[2:3], 12
	v_ashrrev_i32_e32 v225, 31, v224
	s_or_b32 s2, s2, s34
	v_lshlrev_b64 v[224:225], s40, v[224:225]
	v_add_u32_e32 v228, s33, v113
	v_lshl_add_u64 v[232:233], v[224:225], 0, s[2:3]
	v_mov_b64_e32 v[224:225], s[68:69]
	v_ashrrev_i32_e32 v229, 31, v228
	v_mad_u64_u32 v[226:227], s[34:35], v232, s1, v[224:225]
	v_mul_lo_u32 v234, v233, s1
	s_lshl_b32 s12, s12, 7
	v_lshlrev_b64 v[228:229], s40, v[228:229]
	v_add_u32_e32 v227, v234, v227
	s_and_b32 s12, s12, 0x380
	v_lshl_add_u64 v[240:241], v[228:229], 0, s[2:3]
	v_lshl_add_u64 v[226:227], v[226:227], 0, s[12:13]
	v_mov_b32_e32 v117, v115
	v_mad_u64_u32 v[224:225], s[2:3], v240, s1, v[224:225]
	v_mul_lo_u32 v248, v241, s1
	v_lshl_add_u64 v[226:227], v[226:227], 0, v[116:117]
	v_add_u32_e32 v225, v248, v225
	v_add_co_u32_e32 v226, vcc, s9, v226
	v_lshl_add_u64 v[224:225], v[224:225], 0, s[12:13]
	s_nop 0
	v_addc_co_u32_e32 v227, vcc, 0, v227, vcc
	v_lshl_add_u64 v[224:225], v[224:225], 0, v[116:117]
	v_add_co_u32_e32 v228, vcc, s9, v224
	v_lshl_add_u64 v[242:243], v[120:121], 0, s[12:13]
	s_nop 0
	v_addc_co_u32_e32 v229, vcc, 0, v225, vcc
	v_mad_u64_u32 v[232:233], s[2:3], v232, s1, v[242:243]
	v_add_u32_e32 v233, v234, v233
	v_add_co_u32_e32 v236, vcc, 0x1000, v232
	v_mad_u64_u32 v[240:241], s[2:3], v240, s1, v[242:243]
	s_nop 0
	v_addc_co_u32_e32 v237, vcc, 0, v233, vcc
	v_add_u32_e32 v241, v248, v241
	v_add_co_u32_e32 v248, vcc, 0x1000, v240
	global_load_dwordx4 v[224:227], v[226:227], off
	s_nop 0
	global_load_dwordx4 v[228:231], v[228:229], off
	v_addc_co_u32_e32 v249, vcc, 0, v241, vcc
	global_load_dwordx4 v[232:235], v[236:237], off offset:1024
	s_nop 0
	global_load_dwordx4 v[236:239], v[236:237], off offset:2048
	s_nop 0
	global_load_dwordx4 v[240:243], v[248:249], off offset:1024
	s_nop 0
	global_load_dwordx4 v[248:251], v[248:249], off offset:2048
	s_mov_b64 s[2:3], s[60:61]
	s_sub_i32 s17, s16, s0
	s_lshl_b32 s12, s17, 7
	s_and_b32 s12, s12, 0x80
	v_add_u32_e32 v40, s12, v112
	v_mad_u64_u32 v[40:41], s[14:15], v40, s18, v[118:119]
	s_barrier
	s_waitcnt vmcnt(11)
	ds_write_b128 v140, v[12:15]
	s_waitcnt vmcnt(9)
	ds_write_b128 v40, v[24:27] offset:18432
	s_waitcnt vmcnt(8)
	ds_write_b128 v40, v[28:31] offset:55296
	ds_write_b128 v141, v[20:23]
	v_add_u32_e32 v40, s12, v113
	v_mad_u64_u32 v[40:41], s[14:15], v40, s18, v[118:119]
	s_andn2_b64 vcc, exec, s[2:3]
	s_waitcnt vmcnt(7)
	ds_write_b128 v40, v[32:35] offset:18432
	s_waitcnt vmcnt(6)
	ds_write_b128 v40, v[36:39] offset:55296
	s_cbranch_vccnz .LBB0_409
	s_branch .Lpf_bb408
.LBB0_406:
	s_or_b64 exec, exec, s[2:3]
	s_mov_b64 s[2:3], 0
	s_and_b64 vcc, exec, s[14:15]
	s_mov_b32 s16, s31
	s_cbranch_vccnz .LBB0_419
	s_xor_b32 s53, s53, 1
	s_cmp_lg_u32 s32, 0
	s_cbranch_scc1 .Lpf_topB1
	s_bitcmp1_b32 s53, 0
	s_cbranch_scc1 .Lpf_topB
	s_sub_i32 s17, s16, s0
	s_lshl_b32 s12, s17, 7
	s_and_b32 s12, s12, 0x80
	v_add_u32_e32 v40, s12, v112
	v_mad_u64_u32 v[40:41], s[14:15], v40, s18, v[118:119]
	s_barrier
	s_waitcnt vmcnt(13)
	ds_write_b128 v140, v[12:15]
	s_waitcnt vmcnt(11)
	ds_write_b128 v40, v[24:27] offset:18432
	s_waitcnt vmcnt(10)
	ds_write_b128 v40, v[28:31] offset:55296
	ds_write_b128 v141, v[20:23]
	v_add_u32_e32 v40, s12, v113
	v_mad_u64_u32 v[40:41], s[14:15], v40, s18, v[118:119]
	s_waitcnt vmcnt(9)
	ds_write_b128 v40, v[32:35] offset:18432
	s_waitcnt vmcnt(8)
	ds_write_b128 v40, v[36:39] offset:55296
	s_branch .LBB0_409
.Lpf_topB:
	s_sub_i32 s17, s16, s0
	s_lshl_b32 s12, s17, 7
	s_and_b32 s12, s12, 0x80
	v_add_u32_e32 v40, s12, v112
	v_mad_u64_u32 v[40:41], s[14:15], v40, s18, v[118:119]
	s_barrier
	s_waitcnt vmcnt(13)
	ds_write_b128 v140, v[224:227]
	s_waitcnt vmcnt(11)
	ds_write_b128 v40, v[232:235] offset:18432
	s_waitcnt vmcnt(10)
	ds_write_b128 v40, v[236:239] offset:55296
	ds_write_b128 v141, v[228:231]
	v_add_u32_e32 v40, s12, v113
	v_mad_u64_u32 v[40:41], s[14:15], v40, s18, v[118:119]
	s_waitcnt vmcnt(9)
	ds_write_b128 v40, v[240:243] offset:18432
	s_waitcnt vmcnt(8)
	ds_write_b128 v40, v[248:251] offset:55296
	s_branch .LBB0_409
.Lpf_topB1:
	s_mov_b32 s32, 0
	s_sub_i32 s17, s16, s0
	s_lshl_b32 s12, s17, 7
	s_and_b32 s12, s12, 0x80
	v_add_u32_e32 v40, s12, v112
	v_mad_u64_u32 v[40:41], s[14:15], v40, s18, v[118:119]
	s_barrier
	s_waitcnt vmcnt(9)
	ds_write_b128 v140, v[224:227]
	s_waitcnt vmcnt(7)
	ds_write_b128 v40, v[232:235] offset:18432
	s_waitcnt vmcnt(6)
	ds_write_b128 v40, v[236:239] offset:55296
	ds_write_b128 v141, v[228:231]
	v_add_u32_e32 v40, s12, v113
	v_mad_u64_u32 v[40:41], s[14:15], v40, s18, v[118:119]
	s_waitcnt vmcnt(5)
	ds_write_b128 v40, v[240:243] offset:18432
	s_waitcnt vmcnt(4)
	ds_write_b128 v40, v[248:251] offset:55296
	s_branch .LBB0_409

.Lpf_bb408:
	s_xor_b32 s12, s12, 0x80
	v_add_u32_e32 v40, s12, v112
	v_mad_u64_u32 v[40:41], s[2:3], v40, s18, v[118:119]
	ds_write_b128 v40, v[0:3] offset:18432
	ds_write_b128 v40, v[4:7] offset:55296
	v_add_u32_e32 v40, s12, v113
	v_mad_u64_u32 v[40:41], s[2:3], v40, s18, v[118:119]
	ds_write_b128 v40, v[8:11] offset:18432
	ds_write_b128 v40, v[16:19] offset:55296
.LBB0_409:
	s_add_i32 s31, s16, 1
	s_cmp_ge_i32 s31, s8
	s_cselect_b64 s[14:15], -1, 0
	s_and_b64 vcc, exec, s[14:15]
	s_waitcnt lgkmcnt(0)
	s_barrier
	s_add_i32 s59, s16, 2
	s_cmp_ge_i32 s59, s8
	s_cbranch_scc1 .LBB0_411
	s_bitcmp1_b32 s53, 0
	s_cbranch_scc1 .Lpf_B
	s_mul_hi_i32 s2, s59, 0x2aaaaaab
	s_lshr_b32 s3, s2, 31
	s_ashr_i32 s2, s2, 4
	s_add_i32 s12, s2, s3
	s_mul_i32 s2, s12, 0xffffffa0
	s_add_i32 s3, s2, s59
	s_ashr_i32 s3, s3, 4
	s_and_b32 s40, s3, -2
	s_and_b32 s33, s59, 31
	s_sub_i32 s34, 5, s40
	s_lshr_b32 s3, 32, s40
	s_lshr_b32 s34, s33, s34
	s_mul_i32 s3, s34, s3
	s_sub_i32 s3, s33, s3
	s_ashr_i32 s2, s12, 3
	s_lshl_b32 s33, s3, 7
	s_ashr_i32 s3, s2, 31
	v_add_u32_e32 v12, s33, v112
	s_lshl_b64 s[2:3], s[2:3], 12
	v_ashrrev_i32_e32 v13, 31, v12
	s_or_b32 s2, s2, s34
	v_lshlrev_b64 v[12:13], s40, v[12:13]
	v_add_u32_e32 v20, s33, v113
	v_lshl_add_u64 v[24:25], v[12:13], 0, s[2:3]
	v_mov_b64_e32 v[12:13], s[68:69]
	v_ashrrev_i32_e32 v21, 31, v20
	v_mad_u64_u32 v[14:15], s[34:35], v24, s1, v[12:13]
	v_mul_lo_u32 v26, v25, s1
	s_lshl_b32 s12, s12, 7
	v_lshlrev_b64 v[20:21], s40, v[20:21]
	v_add_u32_e32 v15, v26, v15
	s_and_b32 s12, s12, 0x380
	v_lshl_add_u64 v[32:33], v[20:21], 0, s[2:3]
	v_lshl_add_u64 v[14:15], v[14:15], 0, s[12:13]
	v_mov_b32_e32 v117, v115
	v_mad_u64_u32 v[12:13], s[2:3], v32, s1, v[12:13]
	v_mul_lo_u32 v36, v33, s1
	v_lshl_add_u64 v[14:15], v[14:15], 0, v[116:117]
	v_add_u32_e32 v13, v36, v13
	v_add_co_u32_e32 v14, vcc, s9, v14
	v_lshl_add_u64 v[12:13], v[12:13], 0, s[12:13]
	s_nop 0
	v_addc_co_u32_e32 v15, vcc, 0, v15, vcc
	v_lshl_add_u64 v[12:13], v[12:13], 0, v[116:117]
	v_add_co_u32_e32 v20, vcc, s9, v12
	v_lshl_add_u64 v[34:35], v[120:121], 0, s[12:13]
	s_nop 0
	v_addc_co_u32_e32 v21, vcc, 0, v13, vcc
	v_mad_u64_u32 v[24:25], s[2:3], v24, s1, v[34:35]
	v_add_u32_e32 v25, v26, v25
	v_add_co_u32_e32 v28, vcc, 0x1000, v24
	v_mad_u64_u32 v[32:33], s[2:3], v32, s1, v[34:35]
	s_nop 0
	v_addc_co_u32_e32 v29, vcc, 0, v25, vcc
	v_add_u32_e32 v33, v36, v33
	v_add_co_u32_e32 v36, vcc, 0x1000, v32
	global_load_dwordx4 v[12:15], v[14:15], off
	s_nop 0
	global_load_dwordx4 v[20:23], v[20:21], off
	v_addc_co_u32_e32 v37, vcc, 0, v33, vcc
	global_load_dwordx4 v[24:27], v[28:29], off offset:1024
	s_nop 0
	global_load_dwordx4 v[28:31], v[28:29], off offset:2048
	s_nop 0
	global_load_dwordx4 v[32:35], v[36:37], off offset:1024
	s_nop 0
	global_load_dwordx4 v[36:39], v[36:37], off offset:2048
	s_branch .LBB0_411
.Lpf_B:
	s_mul_hi_i32 s2, s59, 0x2aaaaaab
	s_lshr_b32 s3, s2, 31
	s_ashr_i32 s2, s2, 4
	s_add_i32 s12, s2, s3
	s_mul_i32 s2, s12, 0xffffffa0
	s_add_i32 s3, s2, s59
	s_ashr_i32 s3, s3, 4
	s_and_b32 s40, s3, -2
	s_and_b32 s33, s59, 31
	s_sub_i32 s34, 5, s40
	s_lshr_b32 s3, 32, s40
	s_lshr_b32 s34, s33, s34
	s_mul_i32 s3, s34, s3
	s_sub_i32 s3, s33, s3
	s_ashr_i32 s2, s12, 3
	s_lshl_b32 s33, s3, 7
	s_ashr_i32 s3, s2, 31
	v_add_u32_e32 v224, s33, v112
	s_lshl_b64 s[2:3], s[2:3], 12
	v_ashrrev_i32_e32 v225, 31, v224
	s_or_b32 s2, s2, s34
	v_lshlrev_b64 v[224:225], s40, v[224:225]
	v_add_u32_e32 v228, s33, v113
	v_lshl_add_u64 v[232:233], v[224:225], 0, s[2:3]
	v_mov_b64_e32 v[224:225], s[68:69]
	v_ashrrev_i32_e32 v229, 31, v228
	v_mad_u64_u32 v[226:227], s[34:35], v232, s1, v[224:225]
	v_mul_lo_u32 v234, v233, s1
	s_lshl_b32 s12, s12, 7
	v_lshlrev_b64 v[228:229], s40, v[228:229]
	v_add_u32_e32 v227, v234, v227
	s_and_b32 s12, s12, 0x380
	v_lshl_add_u64 v[240:241], v[228:229], 0, s[2:3]
	v_lshl_add_u64 v[226:227], v[226:227], 0, s[12:13]
	v_mov_b32_e32 v117, v115
	v_mad_u64_u32 v[224:225], s[2:3], v240, s1, v[224:225]
	v_mul_lo_u32 v248, v241, s1
	v_lshl_add_u64 v[226:227], v[226:227], 0, v[116:117]
	v_add_u32_e32 v225, v248, v225
	v_add_co_u32_e32 v226, vcc, s9, v226
	v_lshl_add_u64 v[224:225], v[224:225], 0, s[12:13]
	s_nop 0
	v_addc_co_u32_e32 v227, vcc, 0, v227, vcc
	v_lshl_add_u64 v[224:225], v[224:225], 0, v[116:117]
	v_add_co_u32_e32 v228, vcc, s9, v224
	v_lshl_add_u64 v[242:243], v[120:121], 0, s[12:13]
	s_nop 0
	v_addc_co_u32_e32 v229, vcc, 0, v225, vcc
	v_mad_u64_u32 v[232:233], s[2:3], v232, s1, v[242:243]
	v_add_u32_e32 v233, v234, v233
	v_add_co_u32_e32 v236, vcc, 0x1000, v232
	v_mad_u64_u32 v[240:241], s[2:3], v240, s1, v[242:243]
	s_nop 0
	v_addc_co_u32_e32 v237, vcc, 0, v233, vcc
	v_add_u32_e32 v241, v248, v241
	v_add_co_u32_e32 v248, vcc, 0x1000, v240
	global_load_dwordx4 v[224:227], v[226:227], off
	s_nop 0
	global_load_dwordx4 v[228:231], v[228:229], off
	v_addc_co_u32_e32 v249, vcc, 0, v241, vcc
	global_load_dwordx4 v[232:235], v[236:237], off offset:1024
	s_nop 0
	global_load_dwordx4 v[236:239], v[236:237], off offset:2048
	s_nop 0
	global_load_dwordx4 v[240:243], v[248:249], off offset:1024
	s_nop 0
	global_load_dwordx4 v[248:251], v[248:249], off offset:2048
